# hoist LDS-DMA scalar preamble out of the softmax-0 slot into loop head / PV1 MFMA gaps
# speedup vs baseline: 1.0075x; 1.0075x over previous
.LBB0_1278:
	s_cmp_le_i32 s35, s89
	s_cselect_b64 s[70:71], -1, 0
	s_cmp_gt_i32 s35, s89
	s_cbranch_scc1 .LBB0_1288
	s_and_b32 vcc_lo, s35, 1
	s_mul_i32 vcc_hi, vcc_lo, 0x4800
	v_add_u32_e32 v237, vcc_hi, v234
	v_add_u32_e32 v217, 0xd000, v237
	s_mulk_i32 vcc_lo, 0x6800
	s_add_i32 vcc_lo, vcc_lo, 0
	s_and_b32 s99, s34, 1
	s_mul_i32 s98, s99, 0x4800
	s_addk_i32 s98, 0x6800
	s_mulk_i32 s99, 0x6800
	s_add_i32 s99, s99, s44
	s_add_i32 s98, s98, s44
	s_lshl_b32 s94, s34, 18
	s_lshl_b32 s90, s34, 13
	s_lshl_b32 s91, s34, 7
	s_lshl_b32 s92, s34, s95
.Lfh:
	s_setprio 1
	s_waitcnt lgkmcnt(8)
	v_mfma_f32_32x32x16_bf16 v[64:79], v[168:171], v[80:83], v[238:253]
	ds_read_b128 v[180:183], v237 offset:53248
	ds_read_b128 v[176:179], v237 offset:53280
	v_add_u32_e32 v172, vcc_lo, v229
	v_add_u32_e32 v218, vcc_lo, v233
	v_mfma_f32_32x32x16_bf16 v[64:79], v[160:163], v[84:87], v[64:79]
	ds_read_b128 v[196:199], v237 offset:57856
	ds_read_b128 v[188:191], v237 offset:62464
	v_mfma_f32_32x32x16_bf16 v[64:79], v[164:167], v[88:91], v[64:79]
	ds_read_b128 v[200:203], v217 offset:13824
	ds_read_b128 v[184:187], v217 offset:13856
	v_mfma_f32_32x32x16_bf16 v[64:79], v[152:155], v[92:95], v[64:79]
	ds_read_b128 v[204:207], v237 offset:57888
	ds_read_b128 v[192:195], v237 offset:62496
	s_waitcnt lgkmcnt(8)
	v_mfma_f32_32x32x16_bf16 v[64:79], v[156:159], v[96:99], v[64:79]
	ds_read_b128 v[168:171], v172 offset:8704
	ds_read_b128 v[160:163], v172 offset:8736
	v_mfma_f32_32x32x16_bf16 v[64:79], v[128:131], v[100:103], v[64:79]
	ds_read_b128 v[164:167], v172 offset:8768
	ds_read_b128 v[152:155], v172 offset:8800
	v_mfma_f32_32x32x16_bf16 v[64:79], v[132:135], v[104:107], v[64:79]
	ds_read_b128 v[156:159], v172 offset:8832
	ds_read_b128 v[128:131], v172 offset:8864
	v_mfma_f32_32x32x16_bf16 v[64:79], v[136:139], v[108:111], v[64:79]
	ds_read_b128 v[132:135], v172 offset:8896
	ds_read_b128 v[136:139], v172 offset:8928
	v_mfma_f32_32x32x16_bf16 v[64:79], v[140:143], v[112:115], v[64:79]
	ds_read_b128 v[140:143], v218 offset:22016
	ds_read_b128 v[172:175], v218 offset:22112
	v_mfma_f32_32x32x16_bf16 v[64:79], v[144:147], v[116:119], v[64:79]
	ds_read_b128 v[144:147], v218 offset:22048
	v_mfma_f32_32x32x16_bf16 v[64:79], v[148:151], v[120:123], v[64:79]
	ds_read_b128 v[148:151], v218 offset:22080
	v_mfma_f32_32x32x16_bf16 v[64:79], v[208:211], v[124:127], v[64:79]
	s_setprio 0
	s_barrier
	s_and_b64 vcc, exec, s[68:69]
	s_cbranch_vccnz .Ldmq_end
	s_cmp_ge_u32 s85, 4
	s_cbranch_scc1 .Lxdq_y
	s_add_i32 m0, s99, 0x0
	v_add_u32_e32 v255, s94, v221
	global_load_lds_dwordx4 v255, s[8:9]
	s_add_i32 m0, s99, 0x1000
	v_add_u32_e32 v255, s94, v222
	global_load_lds_dwordx4 v255, s[8:9]
	s_add_i32 m0, s99, 0x2000
	v_add_u32_e32 v255, s94, v223
	global_load_lds_dwordx4 v255, s[8:9]
	s_add_i32 m0, s99, 0x3000
	v_add_u32_e32 v255, s94, v224
	global_load_lds_dwordx4 v255, s[8:9]
	s_add_i32 m0, s99, 0x4000
	v_add_u32_e32 v255, s92, v225
	global_load_lds_dwordx4 v255, s[46:47]
	s_add_i32 m0, s99, 0x5000
	v_add_u32_e32 v255, s90, v226
	global_load_lds_dwordx4 v255, s[52:53]
	s_branch .Ldmq_end
.Lxdq_y:
	s_lshl_b32 s92, s34, s96
	s_cmp_ge_u32 s45, 2
	s_cselect_b32 s93, s98, s99
	s_add_i32 m0, s93, 0x6000
	v_add_u32_e32 v255, s92, v221
	global_load_lds_dwordx4 v255, s[50:51]
	s_add_i32 m0, s98, 0x7000
	v_add_u32_e32 v255, s91, v222
	global_load_lds_dwordx4 v255, s[54:55]
	s_add_i32 m0, s98, 0x8000
	v_add_u32_e32 v255, s91, v223
	global_load_lds_dwordx4 v255, s[54:55]
	s_add_i32 m0, s98, 0x9000
	v_add_u32_e32 v255, s91, v224
	global_load_lds_dwordx4 v255, s[54:55]
	s_add_i32 m0, s98, 0xa000
	v_add_u32_e32 v255, s91, v225
	global_load_lds_dwordx4 v255, s[54:55]

.LBB0_1289:
	s_cmp_ge_i32 s35, s89
	s_waitcnt vmcnt(0) lgkmcnt(0)
	s_cselect_b64 vcc, -1, 0
	s_or_b64 s[68:69], vcc, s[68:69]
	s_andn2_b64 s[100:101], s[70:71], s[68:69]
	s_bitcmp1_b32 s34, 0
	s_cselect_b32 s99, 0x6800, 0
	s_cselect_b32 s98, 0x4800, 0
	v_add_u32_e32 v72, s99, v230
	v_add_u32_e32 v73, s99, v231
	v_add_u32_e32 v237, s98, v234
	v_add_u32_e32 v217, 0xd000, v237
	s_and_b64 vcc, exec, s[100:101]
	s_waitcnt vmcnt(0) lgkmcnt(0)
	s_barrier
	s_cbranch_vccz .Lpp_slow
	s_setprio 1
	v_mfma_f32_32x32x16_bf16 v[48:63], v[180:183], v[64:67], v[48:63]
	ds_read_b128 v[168:171], v72
	ds_read_b128 v[160:163], v72 offset:32
	v_mfma_f32_32x32x16_bf16 v[32:47], v[184:187], v[64:67], v[32:47]
	ds_read_b128 v[164:167], v72 offset:64
	ds_read_b128 v[152:155], v72 offset:96
	s_add_i32 s15, s15, 64
	s_mov_b32 s35, s34
	v_mfma_f32_32x32x16_bf16 v[16:31], v[192:195], v[64:67], v[16:31]
	ds_read_b128 v[156:159], v72 offset:128
	ds_read_b128 v[128:131], v72 offset:160
	s_add_i32 s34, s34, 1
	s_cmp_ge_u32 s34, s87
	v_mfma_f32_32x32x16_bf16 v[0:15], v[196:199], v[64:67], v[0:15]
	ds_read_b128 v[132:135], v72 offset:192
	ds_read_b128 v[136:139], v72 offset:224
	s_cselect_b64 s[68:69], -1, 0
	s_mov_b64 s[70:71], -1
	v_mfma_f32_32x32x16_bf16 v[48:63], v[176:179], v[68:71], v[48:63]
	ds_read_b128 v[140:143], v73 offset:17408
	ds_read_b128 v[144:147], v73 offset:17440
	s_mov_b32 vcc_lo, s99
	s_and_b32 s99, s34, 1
	s_mul_i32 s98, s99, 0x4800
	s_addk_i32 s98, 0x6800
	v_mfma_f32_32x32x16_bf16 v[32:47], v[200:203], v[68:71], v[32:47]
	ds_read_b128 v[148:151], v73 offset:17472
	ds_read_b128 v[208:211], v73 offset:17504
	s_mulk_i32 s99, 0x6800
	s_add_i32 s99, s99, s44
	s_add_i32 s98, s98, s44
	v_mfma_f32_32x32x16_bf16 v[16:31], v[204:207], v[68:71], v[16:31]
	s_lshl_b32 s94, s34, 18
	s_lshl_b32 s90, s34, 13
	s_lshl_b32 s91, s34, 7
	s_lshl_b32 s92, s34, s95
	v_mfma_f32_32x32x16_bf16 v[0:15], v[188:191], v[68:71], v[0:15]
	s_branch .Lfh
